# chunk scan tail: next chunk's LDS staging issued under the partial-sum reads; per-token rstd by v_rsq_f32 plus one Newton step
# speedup vs baseline: 1.0008x; 1.0008x over previous
.LBB0_1041:
	s_bitcmp1_b32 s15, 0
	s_cselect_b32 s8, 0xf400, 0
	s_add_i32 s8, s8, 0
	v_add_u32_e32 v222, s8, v135
	v_add_u32_e32 v87, v222, v102
	ds_read_b128 v[82:85], v87
	ds_read_b128 v[92:95], v87 offset:64
	v_cvt_pk_bf16_f32 v78, v58, v59
	v_cvt_pk_bf16_f32 v79, v60, v61
	v_cvt_pk_bf16_f32 v80, v54, v55
	v_cvt_pk_bf16_f32 v81, v56, v57
	ds_read_b128 v[166:169], v87 offset:128
	ds_read_b128 v[170:173], v87 offset:192
	v_cvt_pk_bf16_f32 v88, v50, v51
	s_waitcnt lgkmcnt(3)
	v_mfma_f32_16x16x32_bf16 v[82:85], v[82:85], v[78:81], 0
	v_cvt_pk_bf16_f32 v89, v52, v53
	v_cvt_pk_bf16_f32 v90, v46, v47
	v_cvt_pk_bf16_f32 v91, v48, v49
	ds_read_b128 v[174:177], v87 offset:4352
	v_cvt_pk_bf16_f32 v96, v42, v43
	s_waitcnt lgkmcnt(3)
	v_mfma_f32_16x16x32_bf16 v[82:85], v[92:95], v[88:91], v[82:85]
	v_cvt_pk_bf16_f32 v97, v44, v45
	v_cvt_pk_bf16_f32 v98, v38, v39
	v_cvt_pk_bf16_f32 v99, v40, v41
	v_cvt_pk_bf16_f32 v92, v30, v31
	v_cvt_pk_bf16_f32 v93, v32, v33
	s_waitcnt lgkmcnt(2)
	v_mfma_f32_16x16x32_bf16 v[82:85], v[166:169], v[96:99], v[82:85]
	ds_read_b128 v[166:169], v87 offset:4416
	v_cvt_pk_bf16_f32 v94, v34, v35
	v_cvt_pk_bf16_f32 v95, v36, v37
	v_add3_u32 v100, s8, v102, v135
	ds_read_b128 v[178:181], v100 offset:8832
	s_waitcnt lgkmcnt(3)
	v_mfma_f32_16x16x32_bf16 v[82:85], v[170:173], v[92:95], v[82:85]
	v_add_u32_e32 v101, v222, v138
	ds_read_b128 v[182:185], v101 offset:8832
	s_waitcnt vmcnt(22)
	v_mov_b32_e32 v223, v152
	s_waitcnt lgkmcnt(3)
	v_mfma_f32_16x16x32_bf16 v[170:173], v[174:177], v[78:81], 0
	ds_read_b128 v[174:177], v87 offset:4480
	s_waitcnt vmcnt(21)
	v_mov_b32_e32 v224, v153
	s_waitcnt vmcnt(20)
	v_mov_b32_e32 v225, v154
	s_waitcnt lgkmcnt(3)
	v_mfma_f32_16x16x32_bf16 v[166:169], v[166:169], v[88:91], v[170:173]
	s_waitcnt vmcnt(19)
	v_mov_b32_e32 v226, v155
	s_nop 0
	ds_read_b128 v[170:173], v87 offset:4544
	s_waitcnt lgkmcnt(1)
	v_mfma_f32_16x16x32_bf16 v[166:169], v[174:177], v[96:99], v[166:169]
	ds_read_b128 v[174:177], v100 offset:8704
	s_waitcnt lgkmcnt(1)
	v_mfma_f32_16x16x32_bf16 v[166:169], v[170:173], v[92:95], v[166:169]
	ds_read_b128 v[170:173], v100 offset:8768
	s_waitcnt lgkmcnt(1)
	v_mfma_f32_16x16x32_bf16 v[174:177], v[174:177], v[78:81], 0
	s_waitcnt lgkmcnt(0)
	v_mfma_f32_16x16x32_bf16 v[170:173], v[170:173], v[88:91], v[174:177]
	s_nop 5
	ds_read_b128 v[174:177], v100 offset:8896
	v_mfma_f32_16x16x32_bf16 v[170:173], v[178:181], v[96:99], v[170:173]
	ds_read_b128 v[178:181], v101 offset:8704
	s_waitcnt lgkmcnt(1)
	v_mfma_f32_16x16x32_bf16 v[170:173], v[174:177], v[92:95], v[170:173]
	ds_read_b128 v[174:177], v101 offset:8768
	s_waitcnt lgkmcnt(1)
	v_mfma_f32_16x16x32_bf16 v[178:181], v[178:181], v[78:81], 0
	s_waitcnt lgkmcnt(0)
	v_mfma_f32_16x16x32_bf16 v[174:177], v[174:177], v[88:91], v[178:181]
	s_nop 5
	ds_read_b128 v[178:181], v101 offset:8896
	v_mfma_f32_16x16x32_bf16 v[174:177], v[182:185], v[96:99], v[174:177]
	ds_read_b128 v[182:185], v87 offset:17408
	ds_read_b128 v[186:189], v87 offset:17472
	ds_read_b128 v[190:193], v87 offset:17600
	ds_read_b128 v[152:155], v87 offset:21824
	s_waitcnt lgkmcnt(3)
	v_mfma_f32_16x16x32_bf16 v[182:185], v[182:185], v[78:81], 0
	v_mfma_f32_16x16x32_bf16 v[174:177], v[178:181], v[92:95], v[174:177]
	ds_read_b128 v[178:181], v87 offset:17536
	s_waitcnt lgkmcnt(3)
	v_mfma_f32_16x16x32_bf16 v[182:185], v[186:189], v[88:91], v[182:185]
	ds_read_b128 v[186:189], v87 offset:21760
	s_waitcnt lgkmcnt(1)
	v_mfma_f32_16x16x32_bf16 v[178:181], v[178:181], v[96:99], v[182:185]
	s_waitcnt lgkmcnt(0)
	v_mfma_f32_16x16x32_bf16 v[186:189], v[186:189], v[78:81], 0
	v_mfma_f32_16x16x32_bf16 v[178:181], v[190:193], v[92:95], v[178:181]
	s_nop 1
	ds_read_b128 v[182:185], v87 offset:21888
	ds_read_b128 v[190:193], v87 offset:21952
	ds_read_b128 v[194:197], v100 offset:26112
	ds_read_b128 v[198:201], v100 offset:26176
	ds_read_b128 v[202:205], v100 offset:26240
	ds_read_b128 v[206:209], v100 offset:26304
	ds_read_b128 v[210:213], v101 offset:26112
	ds_read_b128 v[214:217], v101 offset:26176
	v_lshlrev_b32_e32 v100, 16, v156
	v_mfma_f32_16x16x32_bf16 v[152:155], v[152:155], v[88:91], v[186:189]
	s_nop 2
	ds_read_b128 v[186:189], v101 offset:26240
	ds_read_b128 v[218:221], v101 offset:26304
	v_and_b32_e32 v101, 0xffff0000, v156
	v_pk_add_f32 v[100:101], v[100:101], v[82:83] neg_lo:[0,1] neg_hi:[0,1]
	v_lshlrev_b32_e32 v82, 16, v157
	v_and_b32_e32 v83, 0xffff0000, v157
	v_pk_add_f32 v[156:157], v[82:83], v[84:85] neg_lo:[0,1] neg_hi:[0,1]
	s_waitcnt lgkmcnt(7)
	v_mfma_f32_16x16x32_bf16 v[82:85], v[194:197], v[78:81], 0
	v_add_u32_e32 v194, v222, v139
	v_lshlrev_b32_e32 v87, 16, v225
	v_sub_f32_e32 v87, v87, v174
	s_waitcnt lgkmcnt(3)
	v_mfma_f32_16x16x32_bf16 v[78:81], v[210:213], v[78:81], 0
	v_mfma_f32_16x16x32_bf16 v[152:155], v[182:185], v[96:99], v[152:155]
	v_lshlrev_b32_e32 v182, 16, v145
	v_and_b32_e32 v183, 0xffff0000, v145
	v_pk_add_f32 v[182:183], v[182:183], v[166:167] neg_lo:[0,1] neg_hi:[0,1]
	v_lshlrev_b32_e32 v166, 16, v147
	v_mfma_f32_16x16x32_bf16 v[82:85], v[198:201], v[88:91], v[82:85]
	v_and_b32_e32 v167, 0xffff0000, v147
	v_pk_add_f32 v[184:185], v[166:167], v[168:169] neg_lo:[0,1] neg_hi:[0,1]
	v_lshlrev_b32_e32 v166, 16, v223
	s_waitcnt lgkmcnt(2)
	v_mfma_f32_16x16x32_bf16 v[78:81], v[214:217], v[88:91], v[78:81]
	v_and_b32_e32 v167, 0xffff0000, v223
	v_and_b32_e32 v145, 0xffff0000, v225
	v_lshlrev_b32_e32 v147, 16, v226
	v_mfma_f32_16x16x32_bf16 v[152:155], v[190:193], v[92:95], v[152:155]
	v_add_f32_e64 v190, v166, -v170
	v_add_f32_e64 v191, v167, -v171
	v_lshlrev_b32_e32 v166, 16, v224
	v_and_b32_e32 v167, 0xffff0000, v224
	v_pk_add_f32 v[192:193], v[166:167], v[172:173] neg_lo:[0,1] neg_hi:[0,1]
	ds_read_b128 v[88:91], v194 offset:37120
	ds_read_b128 v[166:169], v194 offset:34816
	v_mfma_f32_16x16x32_bf16 v[82:85], v[202:205], v[96:99], v[82:85]
	v_cvt_pk_bf16_f32 v172, v182, v183
	v_cvt_pk_bf16_f32 v173, v184, v185
	ds_read_b128 v[182:185], v194 offset:39424
	s_waitcnt lgkmcnt(4)
	v_mfma_f32_16x16x32_bf16 v[78:81], v[186:189], v[96:99], v[78:81]
	v_and_b32_e32 v170, 0xffff0000, v226
	v_sub_f32_e32 v177, v170, v177
	v_cvt_pk_bf16_f32 v170, v100, v101
	v_cvt_pk_bf16_f32 v171, v156, v157
	v_mfma_f32_16x16x32_bf16 v[82:85], v[206:209], v[92:95], v[82:85]
	v_cvt_pk_bf16_f32 v174, v190, v191
	s_nop 0
	s_nop 0
	s_nop 0
	s_nop 0
	s_waitcnt lgkmcnt(3)
	v_mfma_f32_16x16x32_bf16 v[78:81], v[218:221], v[92:95], v[78:81]
	v_sub_f32_e32 v92, v147, v176
	v_sub_f32_e32 v93, v145, v175
	v_cvt_pk_bf16_f32 v175, v192, v193
	s_waitcnt lgkmcnt(1)
	v_mfma_f32_16x16x32_bf16 v[98:101], v[166:169], v[170:173], v[178:181]
	ds_read_b128 v[166:169], v194 offset:39488
	v_cvt_pk_bf16_f32 v176, v87, v93
	v_cvt_pk_bf16_f32 v177, v92, v177
	v_mfma_f32_16x16x32_bf16 v[94:97], v[88:91], v[170:173], v[152:155]
	s_nop 0
	s_nop 0
	s_nop 0
	s_nop 0
	ds_read_b128 v[152:155], v194 offset:41728
	s_waitcnt lgkmcnt(2)
	v_mfma_f32_16x16x32_bf16 v[82:85], v[182:185], v[170:173], v[82:85]
	v_mov_b32_e32 v182, v129
	s_nop 0
	s_nop 0
	v_pk_mul_f32 v[60:61], v[60:61], v[182:183] op_sel_hi:[1,0]
	s_waitcnt lgkmcnt(1)
	v_mfma_f32_16x16x32_bf16 v[90:93], v[166:169], v[174:177], v[82:85]
	s_nop 2
	ds_read_b128 v[82:85], v194 offset:41792
	ds_read_b128 v[166:169], v194 offset:44032
	v_pk_mul_f32 v[58:59], v[58:59], v[182:183] op_sel_hi:[1,0]
	v_pk_mul_f32 v[56:57], v[56:57], v[182:183] op_sel_hi:[1,0]
	s_waitcnt lgkmcnt(2)
	v_mfma_f32_16x16x32_bf16 v[78:81], v[152:155], v[170:173], v[78:81]
	ds_read_b128 v[152:155], v194 offset:44096
	v_pk_mul_f32 v[54:55], v[54:55], v[182:183] op_sel_hi:[1,0]
	v_pk_mul_f32 v[52:53], v[52:53], v[182:183] op_sel_hi:[1,0]
	s_waitcnt lgkmcnt(2)
	v_mfma_f32_16x16x32_bf16 v[86:89], v[82:85], v[174:177], v[78:81]
	ds_read_b128 v[82:85], v194 offset:46400
	v_pk_mul_f32 v[50:51], v[50:51], v[182:183] op_sel_hi:[1,0]
	ds_read_b128 v[162:165], v194 offset:51008
	ds_read_b128 v[78:81], v194 offset:46336
	s_waitcnt lgkmcnt(4)
	v_mfma_f32_16x16x32_bf16 v[58:61], v[166:169], v[170:173], v[58:61]
	v_add3_u32 v168, s8, v139, v135
	v_pk_mul_f32 v[48:49], v[48:49], v[182:183] op_sel_hi:[1,0]
	v_pk_mul_f32 v[46:47], v[46:47], v[182:183] op_sel_hi:[1,0]
	s_waitcnt lgkmcnt(3)
	v_mfma_f32_16x16x32_bf16 v[58:61], v[152:155], v[174:177], v[58:61]
	ds_read_b128 v[152:155], v194 offset:48640
	v_add_u32_e32 v166, v222, v140
	v_pk_mul_f32 v[44:45], v[44:45], v[182:183] op_sel_hi:[1,0]
	s_waitcnt lgkmcnt(1)
	v_mfma_f32_16x16x32_bf16 v[54:57], v[78:81], v[170:173], v[54:57]
	ds_read_b128 v[78:81], v194 offset:48704
	v_pk_mul_f32 v[42:43], v[42:43], v[182:183] op_sel_hi:[1,0]
	ds_read_b128 v[178:181], v168 offset:57856
	v_mfma_f32_16x16x32_bf16 v[54:57], v[82:85], v[174:177], v[54:57]
	ds_read_b128 v[82:85], v194 offset:50944
	v_pk_mul_f32 v[40:41], v[40:41], v[182:183] op_sel_hi:[1,0]
	v_pk_mul_f32 v[38:39], v[38:39], v[182:183] op_sel_hi:[1,0]
	s_waitcnt lgkmcnt(3)
	v_mfma_f32_16x16x32_bf16 v[50:53], v[152:155], v[170:173], v[50:53]
	s_nop 0
	s_nop 0
	s_nop 0
	s_waitcnt lgkmcnt(2)
	v_mfma_f32_16x16x32_bf16 v[50:53], v[78:81], v[174:177], v[50:53]
	ds_read_b128 v[78:81], v168 offset:53248
	s_nop 0
	v_pk_mul_f32 v[32:33], v[32:33], v[182:183] op_sel_hi:[1,0]
	s_waitcnt lgkmcnt(1)
	v_mfma_f32_16x16x32_bf16 v[46:49], v[82:85], v[170:173], v[46:49]
	ds_read_b128 v[82:85], v168 offset:53312
	v_pk_mul_f32 v[30:31], v[30:31], v[182:183] op_sel_hi:[1,0]
	v_pk_mul_f32 v[36:37], v[36:37], v[182:183] op_sel_hi:[1,0]
	v_mfma_f32_16x16x32_bf16 v[46:49], v[162:165], v[174:177], v[46:49]
	ds_read_b128 v[160:163], v166 offset:53248
	ds_read_b128 v[164:167], v166 offset:53312
	v_pk_mul_f32 v[34:35], v[34:35], v[182:183] op_sel_hi:[1,0]
	s_waitcnt lgkmcnt(3)
	v_mfma_f32_16x16x32_bf16 v[42:45], v[78:81], v[170:173], v[42:45]
	s_nop 0
	s_nop 0
	ds_read_b128 v[70:73], v168 offset:57920
	s_waitcnt lgkmcnt(3)
	v_mfma_f32_16x16x32_bf16 v[42:45], v[82:85], v[174:177], v[42:45]
	s_nop 0
	s_nop 0
	ds_read_b128 v[74:77], v168 offset:60160
	s_waitcnt lgkmcnt(3)
	v_mfma_f32_16x16x32_bf16 v[38:41], v[160:163], v[170:173], v[38:41]
	ds_read_b128 v[158:161], v168 offset:60224
	v_mfma_f32_16x16x32_bf16 v[30:33], v[178:181], v[170:173], v[30:33]
	s_waitcnt lgkmcnt(1)
	v_mfma_f32_16x16x32_bf16 v[34:37], v[74:77], v[170:173], v[34:37]
	v_mfma_f32_16x16x32_bf16 v[30:33], v[70:73], v[174:177], v[30:33]
	v_mul_f32_e32 v184, v98, v98
	v_mul_f32_e32 v185, v99, v99
	v_mul_f32_e32 v186, v100, v100
	v_mul_f32_e32 v187, v101, v101
	v_mfma_f32_16x16x32_bf16 v[38:41], v[164:167], v[174:177], v[38:41]
	v_mul_f32_e32 v188, v94, v94
	v_mul_f32_e32 v189, v95, v95
	v_mul_f32_e32 v190, v96, v96
	v_mul_f32_e32 v191, v97, v97
	s_waitcnt lgkmcnt(0)
	v_mfma_f32_16x16x32_bf16 v[34:37], v[158:161], v[174:177], v[34:37]
	v_mul_f32_e32 v192, v90, v90
	v_mul_f32_e32 v193, v91, v91
	v_mul_f32_e32 v194, v92, v92
	v_mul_f32_e32 v195, v93, v93
	v_mul_f32_e32 v196, v86, v86
	v_mul_f32_e32 v197, v87, v87
	v_mul_f32_e32 v198, v88, v88
	v_mul_f32_e32 v199, v89, v89
	v_add_f32_dpp v70, v184, v184 row_ror:8 row_mask:0xf bank_mask:0xf
	v_add_f32_dpp v71, v185, v185 row_ror:8 row_mask:0xf bank_mask:0xf
	v_add_f32_dpp v72, v186, v186 row_ror:8 row_mask:0xf bank_mask:0xf
	v_add_f32_dpp v73, v187, v187 row_ror:8 row_mask:0xf bank_mask:0xf
	v_add_f32_dpp v74, v188, v188 row_ror:8 row_mask:0xf bank_mask:0xf
	v_add_f32_dpp v75, v189, v189 row_ror:8 row_mask:0xf bank_mask:0xf
	v_add_f32_dpp v76, v190, v190 row_ror:8 row_mask:0xf bank_mask:0xf
	v_add_f32_dpp v77, v191, v191 row_ror:8 row_mask:0xf bank_mask:0xf
	v_add_f32_dpp v70, v192, v192 row_ror:8 row_mask:0xf bank_mask:0xc
	v_add_f32_dpp v71, v193, v193 row_ror:8 row_mask:0xf bank_mask:0xc
	v_add_f32_dpp v72, v194, v194 row_ror:8 row_mask:0xf bank_mask:0xc
	v_add_f32_dpp v73, v195, v195 row_ror:8 row_mask:0xf bank_mask:0xc
	v_add_f32_dpp v74, v196, v196 row_ror:8 row_mask:0xf bank_mask:0xc
	v_add_f32_dpp v75, v197, v197 row_ror:8 row_mask:0xf bank_mask:0xc
	v_add_f32_dpp v76, v198, v198 row_ror:8 row_mask:0xf bank_mask:0xc
	v_add_f32_dpp v77, v199, v199 row_ror:8 row_mask:0xf bank_mask:0xc
	v_add_f32_dpp v184, v70, v70 row_half_mirror row_mask:0xf bank_mask:0x5
	v_add_f32_dpp v185, v71, v71 row_half_mirror row_mask:0xf bank_mask:0x5
	v_add_f32_dpp v186, v72, v72 row_half_mirror row_mask:0xf bank_mask:0x5
	v_add_f32_dpp v187, v73, v73 row_half_mirror row_mask:0xf bank_mask:0x5
	v_add_f32_dpp v184, v74, v74 row_half_mirror row_mask:0xf bank_mask:0xa
	v_add_f32_dpp v185, v75, v75 row_half_mirror row_mask:0xf bank_mask:0xa
	v_add_f32_dpp v186, v76, v76 row_half_mirror row_mask:0xf bank_mask:0xa
	v_add_f32_dpp v187, v77, v77 row_half_mirror row_mask:0xf bank_mask:0xa
	v_add_f32_dpp v70, v184, v184 quad_perm:[2,3,0,1] row_mask:0xf bank_mask:0xf
	v_add_f32_dpp v71, v186, v186 quad_perm:[2,3,0,1] row_mask:0xf bank_mask:0xf
	v_add_f32_dpp v72, v185, v185 quad_perm:[2,3,0,1] row_mask:0xf bank_mask:0xf
	v_add_f32_dpp v73, v187, v187 quad_perm:[2,3,0,1] row_mask:0xf bank_mask:0xf
	v_cndmask_b32_e64 v74, v70, v71, s[100:101]
	v_cndmask_b32_e64 v75, v72, v73, s[100:101]
	s_nop 0
	v_add_f32_dpp v76, v74, v74 quad_perm:[1,0,3,2] row_mask:0xf bank_mask:0xf
	v_add_f32_dpp v77, v75, v75 quad_perm:[1,0,3,2] row_mask:0xf bank_mask:0xf
	v_add3_u32 v200, s3, v135, v251
	v_cndmask_b32_e64 v76, v76, v77, s[98:99]
	ds_write_b32 v200, v76
	s_waitcnt lgkmcnt(0)
	s_barrier
	ds_read_b32 v70, v227
	ds_read_b32 v71, v227 offset:256
	ds_read_b32 v72, v227 offset:512
	ds_read_b32 v73, v227 offset:768
	ds_read_b32 v74, v227 offset:1024
	ds_read_b32 v75, v227 offset:1280
	ds_read_b32 v76, v227 offset:1536
	ds_read_b32 v77, v227 offset:1792
	s_add_i32 s8, s15, 1
	s_cmp_eq_u32 s15, 31
	s_cbranch_scc1 .Lsc_nostore
	s_bitcmp1_b32 s8, 0
	s_cselect_b32 s9, 0xf400, 0
	s_add_i32 s9, s9, 0
	v_add_u32_e32 v242, s9, v130
	s_waitcnt vmcnt(9)
	ds_write_b128 v242, v[2:5]
	ds_write_b128 v242, v[6:9] offset:17408
	v_add_u32_e32 v242, s9, v131
	v_add_u32_e32 v243, s9, v132
	ds_write_b128 v242, v[10:13] offset:44032
	ds_write_b128 v243, v[14:17]
	ds_write_b128 v243, v[18:21] offset:17408
	v_add_u32_e32 v243, s9, v133
	ds_write_b128 v243, v[22:25] offset:44032
	ds_write_b128 v242, v[26:29] offset:34816
	s_waitcnt lgkmcnt(7)
	s_branch .Lsc_join

.Lsc_join:
	v_add_f32_e32 v70, v70, v71
	v_add_f32_e32 v72, v72, v73
	v_add_f32_e32 v74, v74, v75
	v_add_f32_e32 v76, v76, v77
	v_add_f32_e32 v70, v70, v72
	v_add_f32_e32 v74, v74, v76
	v_add_f32_e32 v70, v70, v74
	v_fmamk_f32 v70, v70, 0x3c000000, v146
	v_rsq_f32_e32 v71, v70
	s_nop 0
	v_mul_f32_e32 v72, v70, v71
	v_fma_f32 v72, -v72, v71, 1.0
	v_mul_f32_e32 v73, 0.5, v71
	v_fma_f32 v229, v73, v72, v71
.LBB0_1075:
.LBB0_1077:
	s_waitcnt lgkmcnt(0)
	s_nop 0
	ds_bpermute_b32 v70, v228, v229 offset:0
	ds_bpermute_b32 v71, v228, v229 offset:4
	ds_bpermute_b32 v72, v228, v229 offset:8
	ds_bpermute_b32 v73, v228, v229 offset:12
	ds_bpermute_b32 v74, v228, v229 offset:64
	ds_bpermute_b32 v75, v228, v229 offset:68
	ds_bpermute_b32 v76, v228, v229 offset:72
	ds_bpermute_b32 v77, v228, v229 offset:76
	s_cmp_gt_u32 s15, 29
	s_nop 0
	s_nop 0
	s_waitcnt lgkmcnt(4)
	v_mul_f32_e32 v70, v98, v70
	v_mul_f32_e32 v70, v128, v70
	v_mul_f32_e32 v71, v99, v71
	v_cvt_pk_bf16_f32 v70, v70, s0
	ds_write_b16 v149, v70
	v_mul_f32_e32 v70, v128, v71
	v_cvt_pk_bf16_f32 v70, v70, s0
	ds_write_b16 v149, v70 offset:272
	v_mul_f32_e32 v70, v100, v72
	v_mul_f32_e32 v70, v128, v70
	v_cvt_pk_bf16_f32 v70, v70, s0
	ds_write_b16 v149, v70 offset:544
	v_mul_f32_e32 v70, v101, v73
	v_mul_f32_e32 v70, v128, v70
	v_cvt_pk_bf16_f32 v70, v70, s0
	ds_write_b16 v149, v70 offset:816
	s_waitcnt lgkmcnt(4)
	v_mul_f32_e32 v70, v94, v74
	v_mul_f32_e32 v70, v128, v70
	v_cvt_pk_bf16_f32 v70, v70, s0
	ds_write_b16 v149, v70 offset:4352
	v_mul_f32_e32 v70, v95, v75
	v_mul_f32_e32 v70, v128, v70
	v_cvt_pk_bf16_f32 v70, v70, s0
	ds_write_b16 v149, v70 offset:4624
	v_mul_f32_e32 v70, v96, v76
	v_mul_f32_e32 v70, v128, v70
	v_cvt_pk_bf16_f32 v70, v70, s0
	ds_write_b16 v149, v70 offset:4896
	ds_bpermute_b32 v70, v228, v229 offset:128
	ds_bpermute_b32 v71, v228, v229 offset:132
	ds_bpermute_b32 v72, v228, v229 offset:136
	ds_bpermute_b32 v73, v228, v229 offset:140
	v_mul_f32_e32 v74, v97, v77
	v_mul_f32_e32 v74, v128, v74
	v_cvt_pk_bf16_f32 v74, v74, s0
	ds_write_b16 v149, v74 offset:5168
	ds_bpermute_b32 v74, v228, v229 offset:192
	ds_bpermute_b32 v75, v228, v229 offset:196
	ds_bpermute_b32 v76, v228, v229 offset:200
	ds_bpermute_b32 v77, v228, v229 offset:204
	s_waitcnt lgkmcnt(5)
	v_mul_f32_e32 v70, v90, v70
	v_mul_f32_e32 v70, v128, v70
	v_cvt_pk_bf16_f32 v70, v70, s0
	ds_write_b16 v149, v70 offset:8704
	v_mul_f32_e32 v70, v91, v71
	v_mul_f32_e32 v70, v128, v70
	v_cvt_pk_bf16_f32 v70, v70, s0
	ds_write_b16 v149, v70 offset:8976
	v_mul_f32_e32 v70, v92, v72
	v_mul_f32_e32 v70, v128, v70
	v_cvt_pk_bf16_f32 v70, v70, s0
	ds_write_b16 v149, v70 offset:9248
	v_mul_f32_e32 v70, v93, v73
	v_mul_f32_e32 v70, v128, v70
	v_cvt_pk_bf16_f32 v70, v70, s0
	ds_write_b16 v149, v70 offset:9520
	s_waitcnt lgkmcnt(4)
	v_mul_f32_e32 v70, v86, v74
	v_mul_f32_e32 v70, v128, v70
	v_cvt_pk_bf16_f32 v70, v70, s0
	ds_write_b16 v149, v70 offset:13056
	v_mul_f32_e32 v70, v87, v75
	v_mul_f32_e32 v70, v128, v70
	v_cvt_pk_bf16_f32 v70, v70, s0
	ds_write_b16 v149, v70 offset:13328
	v_mul_f32_e32 v70, v88, v76
	v_mul_f32_e32 v70, v128, v70
	v_cvt_pk_bf16_f32 v70, v70, s0
	ds_write_b16 v149, v70 offset:13600
	v_mul_f32_e32 v70, v89, v77
	v_mul_f32_e32 v70, v128, v70
	v_cvt_pk_bf16_f32 v70, v70, s0
	ds_write_b16 v149, v70 offset:13872
	s_waitcnt lgkmcnt(0)
	s_barrier
	ds_read_b128 v[70:73], v150
	ds_read_b128 v[74:77], v151
	v_lshlrev_b32_e32 v88, 16, v66
	v_and_b32_e32 v89, 0xffff0000, v66
	s_nop 0
	s_waitcnt lgkmcnt(1)
	v_lshlrev_b32_e32 v86, 16, v70
	v_and_b32_e32 v87, 0xffff0000, v70
	v_pk_mul_f32 v[86:87], v[88:89], v[86:87]
	v_lshlrev_b32_e32 v70, 16, v71
	v_cvt_pk_bf16_f32 v66, v86, v87
	v_and_b32_e32 v71, 0xffff0000, v71
	v_lshlrev_b32_e32 v86, 16, v67
	v_and_b32_e32 v87, 0xffff0000, v67
	v_pk_mul_f32 v[70:71], v[86:87], v[70:71]
	v_lshlrev_b32_e32 v86, 16, v68
	v_cvt_pk_bf16_f32 v67, v70, v71
	v_lshlrev_b32_e32 v70, 16, v72
	v_and_b32_e32 v71, 0xffff0000, v72
	v_and_b32_e32 v87, 0xffff0000, v68
	v_pk_mul_f32 v[70:71], v[86:87], v[70:71]
	v_lshlrev_b32_e32 v72, 16, v69
	v_cvt_pk_bf16_f32 v68, v70, v71
	v_lshlrev_b32_e32 v70, 16, v73
	v_and_b32_e32 v71, 0xffff0000, v73
	v_and_b32_e32 v73, 0xffff0000, v69
	v_pk_mul_f32 v[70:71], v[72:73], v[70:71]
	s_nop 0
	v_cvt_pk_bf16_f32 v69, v70, v71
	global_store_dwordx4 v[126:127], v[66:69], off
	s_nop 0
	s_nop 0
	s_waitcnt lgkmcnt(0)
	v_lshlrev_b32_e32 v66, 16, v74
	v_and_b32_e32 v67, 0xffff0000, v74
	v_lshlrev_b32_e32 v68, 16, v62
	v_and_b32_e32 v69, 0xffff0000, v62
	v_pk_mul_f32 v[66:67], v[68:69], v[66:67]
	v_lshlrev_b32_e32 v68, 16, v63
	v_cvt_pk_bf16_f32 v62, v66, v67
	v_lshlrev_b32_e32 v66, 16, v75
	v_and_b32_e32 v67, 0xffff0000, v75
	v_and_b32_e32 v69, 0xffff0000, v63
	v_pk_mul_f32 v[66:67], v[68:69], v[66:67]
	v_lshlrev_b32_e32 v68, 16, v64
	v_cvt_pk_bf16_f32 v63, v66, v67
	v_lshlrev_b32_e32 v66, 16, v76
	v_and_b32_e32 v67, 0xffff0000, v76
	v_and_b32_e32 v69, 0xffff0000, v64
	v_pk_mul_f32 v[66:67], v[68:69], v[66:67]
	v_lshlrev_b32_e32 v68, 16, v65
	v_cvt_pk_bf16_f32 v64, v66, v67
	v_lshlrev_b32_e32 v66, 16, v77
	v_and_b32_e32 v67, 0xffff0000, v77
	v_and_b32_e32 v69, 0xffff0000, v65
	v_pk_mul_f32 v[66:67], v[68:69], v[66:67]
	s_nop 0
	v_cvt_pk_bf16_f32 v65, v66, v67
	s_nop 0
	s_nop 0
	s_nop 0
	s_nop 0
	s_nop 0
	s_nop 0
	global_store_dwordx4 v[124:125], v[62:65], off
	s_waitcnt vmcnt(2)
	v_mov_b32_e32 v129, v250
	v_mov_b32_e32 v156, v230
	v_mov_b32_e32 v157, v231
	v_mov_b32_e32 v145, v232
	v_mov_b32_e32 v147, v233
	v_mov_b32_e32 v152, v234
	v_mov_b32_e32 v153, v235
	v_mov_b32_e32 v154, v236
	v_mov_b32_e32 v155, v237
	v_mov_b64_e32 v[78:79], v[238:239]
	v_mov_b64_e32 v[80:81], v[240:241]
	v_mov_b64_e32 v[82:83], v[246:247]
	v_mov_b64_e32 v[84:85], v[248:249]
	s_cbranch_scc1 .LBB0_1040
	s_add_i32 s18, s20, s15
	s_ashr_i32 s15, s14, 31
	v_lshl_add_u64 v[2:3], s[14:15], 0, v[108:109]
	v_lshlrev_b64 v[14:15], 11, v[2:3]
	v_lshl_add_u64 v[2:3], v[104:105], 0, v[14:15]
	v_lshl_add_u64 v[6:7], v[106:107], 0, v[14:15]
	v_lshl_add_u64 v[14:15], v[116:117], 0, v[14:15]
	s_ashr_i32 s19, s18, 31
	global_load_dwordx4 v[238:241], v[14:15], off nt
	v_lshl_add_u64 v[14:15], s[14:15], 0, v[112:113]
	s_lshl_b64 s[22:23], s[18:19], 14
	v_lshlrev_b64 v[26:27], 11, v[14:15]
	v_lshl_add_u64 v[22:23], v[118:119], 0, s[22:23]
	v_lshl_add_u64 v[14:15], v[104:105], 0, v[26:27]
	v_lshl_add_u64 v[18:19], v[106:107], 0, v[26:27]
	v_lshl_add_u64 v[26:27], v[116:117], 0, v[26:27]
	s_lshl_b64 s[18:19], s[18:19], 13
	v_lshl_add_u64 v[62:63], v[122:123], 0, s[22:23]
	v_lshl_add_u64 v[10:11], v[110:111], 1, v[22:23]
	v_lshl_add_u64 v[22:23], v[114:115], 1, v[22:23]
	global_load_dwordx4 v[246:249], v[26:27], off nt
	v_lshl_add_u64 v[26:27], v[120:121], 0, s[18:19]
	v_lshl_add_u64 v[64:65], s[0:1], 2, v[62:63]
	v_lshl_add_u64 v[62:63], s[10:11], 2, v[62:63]
	global_load_dwordx4 v[2:5], v[2:3], off nt
	s_nop 0
	global_load_dwordx4 v[6:9], v[6:7], off nt
	s_nop 0
	global_load_dwordx4 v[10:13], v[10:11], off nt
	s_nop 0
	global_load_dwordx4 v[14:17], v[14:15], off nt
	s_nop 0
	global_load_dwordx4 v[18:21], v[18:19], off nt
	s_nop 0
	global_load_dwordx4 v[22:25], v[22:23], off nt
	s_nop 0
	global_load_dwordx4 v[26:29], v[26:27], off nt
	s_nop 0
	global_load_dword v230, v[64:65], off nt
	global_load_dword v231, v[62:63], off offset:256 nt
	global_load_dword v232, v[62:63], off offset:512 nt
	global_load_dword v233, v[62:63], off offset:768 nt
	global_load_dword v234, v[62:63], off offset:1024 nt
	global_load_dword v235, v[62:63], off offset:1280 nt
	global_load_dword v236, v[62:63], off offset:1536 nt
	global_load_dword v237, v[62:63], off offset:1792 nt
	global_load_dword v250, v103, s[12:13]
	s_branch .LBB0_1040
